# v10: v9 + GLA chunk loop top wait counted vmcnt(16) so output stores stay in flight
# baseline (speedup 1.0000x reference)
; #define LAS __attribute__((address_space(3)))
; __device__ __forceinline__ void phase_gla(const Frame& F, int l, int gi, int ng, bool last, unsigned* cw) {
;     ...
;     for (int item = gi; item < 128; item += ng) {
;         const int b = item & 7, idx = item >> 3, h = idx >> 2, dir = (idx >> 1) & 1, sl = idx & 1;
;         const float* gwp = (dir ? F.in[17] : F.in[15]) + (size_t)l * 16 * 512 + h * 128;
;         const float* gbp = (dir ? F.in[18] : F.in[16]) + (size_t)l * 512 + h * 128;
;         f16* Oout = dir ? F.OB : F.H16;
;         const int d = tid & 127, tg = tid >> 7;
;         f16x8 gwf;
; #pragma unroll
;         for (int j = 0; j < 8; ++j) gwf[j] = (f16)gwp[(hh * 8 + j) * 512 + (w & 3) * 32 + r32];
;         const float gbv = gbp[(w & 3) * 32 + r32];
;         const int li = tid >> 3, ls = tid & 7;
;         const int vi = tid & 63, vs = tid >> 6;
;         const int it = w >> 2, et = w & 3;
;         const int dt = w >> 1, e2 = (w & 1) * 2;
;         f32x16 Sacc[2];
; #pragma unroll
;         for (int q = 0; q < 2; ++q)
; #pragma unroll
;             for (int e = 0; e < 16; ++e) Sacc[q][e] = 0.f;
;         __syncthreads();
;         for (int i = tid; i < 128 * 136 / 2; i += NTHR) ((LAS unsigned*)(lds + GL_ST))[i] = 0u;
;         u32x4 pq0, pq1, pk0, pk1, pv0, pv1; f32x2 pg;
;         auto chunk_base = [&](int s) -> int { return (s < 4) ? (TL + b * CTXL + (dir ? 3 - s : s) * 64) : (b * SEQ + (dir ? 63 - (s - 4) : (s - 4)) * 64); };
;     ...
;         GLA_LOAD(0);
.LBB0_642:
	s_or_b64 exec, exec, s[2:3]
	s_mov_b64 s[52:53], s[12:13]
	s_and_b32 s13, s16, 7
	s_bfe_u32 s8, s16, 0x10003
	s_mov_b64 s[54:55], s[30:31]
	s_and_b64 s[2:3], s[84:85], exec
	s_cselect_b32 s0, s53, s55
	s_cselect_b32 s12, s52, s54
	s_lshl_b32 s57, s13, 8
	s_or_b32 s88, s57, 0x8000
	s_and_b64 s[2:3], s[84:85], exec
	s_cselect_b32 s2, 0, 0xc0
	s_or_b32 s7, s2, s88
	v_cndmask_b32_e64 v174, v99, v95, s[84:85]
	v_add_u32_e32 v10, s7, v174
	v_mov_b64_e32 v[12:13], s[22:23]
	v_mad_i64_i32 v[12:13], s[2:3], v10, s14, v[12:13]
	v_lshlrev_b32_e32 v110, 1, v94
	v_mov_b32_e32 v111, v1
	v_lshl_add_u64 v[12:13], s[34:35], 1, v[12:13]
	v_lshl_add_u64 v[12:13], v[12:13], 0, v[110:111]
	v_add_co_u32_e32 v16, vcc, s36, v12
	s_mov_b64 s[2:3], 0x1800
	s_nop 0
	v_addc_co_u32_e32 v17, vcc, 0, v13, vcc
	v_cndmask_b32_e64 v175, v120, v161, s[84:85]
	v_writelane_b32 v255, s37, 6
	v_lshl_add_u64 v[14:15], v[12:13], 0, s[2:3]
	global_load_dwordx4 v[70:73], v[16:17], off offset:2048
	global_load_dwordx4 v[74:77], v[14:15], off offset:16
	global_load_dwordx4 v[78:81], v[12:13], off offset:1040
	global_load_dwordx4 v[82:85], v[12:13], off offset:1024
	v_or_b32_e32 v12, s7, v175
	s_lshl_b32 s30, s37, 8
	v_writelane_b32 v255, s8, 7
	v_ashrrev_i32_e32 v11, 31, v10
	v_mul_u32_u24_e32 v12, 0x3400, v12
	v_mov_b32_e32 v13, v1
	s_ashr_i32 s31, s30, 31
	v_readlane_b32 s36, v255, 0
	v_lshl_add_u64 v[12:13], s[22:23], 0, v[12:13]
	s_lshl_b64 s[2:3], s[30:31], 1
	v_lshlrev_b64 v[10:11], 7, v[10:11]
	v_readlane_b32 s37, v255, 1
	v_lshl_add_u64 v[12:13], v[12:13], 0, s[2:3]
	s_lshl_b32 s10, s8, 8
	s_mov_b32 s11, s94
	v_lshl_add_u64 v[10:11], s[36:37], 0, v[10:11]
	s_lshl_b32 s36, s6, 6
	s_mov_b32 s37, s94
	v_lshl_add_u64 v[12:13], v[12:13], 0, s[10:11]
	v_lshl_add_u64 v[10:11], v[10:11], 0, s[36:37]
	v_mov_b32_e32 v107, v1
	v_lshl_add_u64 v[12:13], v[12:13], 0, v[104:105]
	v_lshl_add_u64 v[10:11], v[10:11], 0, v[106:107]
	global_load_dwordx4 v[86:89], v[12:13], off offset:2048
	global_load_dwordx4 v[90:93], v[12:13], off offset:2064
	global_load_dwordx2 v[118:119], v[10:11], off
	s_and_b64 s[6:7], s[84:85], exec
	s_movk_i32 s6, 0xfc00
	s_cselect_b32 s9, 0, -1
	s_cselect_b32 s8, 0x400, s6
	s_add_u32 s6, s12, s2
	s_addc_u32 s0, s0, s3
	s_add_u32 s6, s6, s10
	s_addc_u32 s0, s0, 0
	v_readlane_b32 s7, v255, 5
	s_add_u32 s6, s6, s7
	s_addc_u32 s7, s0, 0
	v_mov_b32_e32 v109, v1
	v_lshl_add_u64 v[112:113], s[6:7], 0, v[108:109]
	s_lshl_b32 s6, s13, 12
	s_add_u32 s0, s22, s2
	s_addc_u32 s3, s23, s3
	s_add_u32 s2, s0, s10
	s_waitcnt vmcnt(14)
	v_cvt_pk_f16_f32 v66, v2, v3
	s_addc_u32 s3, s3, 0
	v_mov_b32_e32 v2, 0
	s_mov_b64 s[58:59], s[18:19]
	s_mov_b64 s[18:19], s[20:21]
	s_mov_b64 s[20:21], s[78:79]
	v_readlane_b32 s78, v254, 60
	s_movk_i32 s1, 0x3400
	s_waitcnt vmcnt(8)
	v_cvt_pk_f16_f32 v69, v8, v9
	v_cvt_pk_f16_f32 v68, v6, v7
	v_cvt_pk_f16_f32 v67, v4, v5
	v_cndmask_b32_e64 v107, v127, v126, s[84:85]
	v_writelane_b32 v255, s13, 8
	v_lshl_add_u64 v[114:115], v[96:97], 0, s[36:37]
	v_lshl_add_u64 v[116:117], s[2:3], 0, v[104:105]
	s_lshl_b64 s[10:11], s[8:9], 1
	s_mul_hi_i32 s87, s8, 10
	s_mul_i32 s86, s8, 10
	s_movk_i32 s37, 0x42
	s_mov_b32 s7, -4
	v_mov_b32_e32 v3, v2
	v_mov_b32_e32 v4, v2
	v_mov_b32_e32 v5, v2
	v_mov_b32_e32 v6, v2
	v_mov_b32_e32 v7, v2
	v_mov_b32_e32 v8, v2
	v_mov_b32_e32 v9, v2
	v_mov_b32_e32 v10, v2
	v_mov_b32_e32 v11, v2
	v_mov_b32_e32 v12, v2
	v_mov_b32_e32 v13, v2
	v_mov_b32_e32 v14, v2
	v_mov_b32_e32 v15, v2
	v_mov_b32_e32 v16, v2
	v_mov_b32_e32 v17, v2
	v_mov_b32_e32 v18, v2
	v_mov_b32_e32 v19, v2
	v_mov_b32_e32 v20, v2
	v_mov_b32_e32 v21, v2
	v_mov_b32_e32 v22, v2
	v_mov_b32_e32 v23, v2
	v_mov_b32_e32 v24, v2
	v_mov_b32_e32 v25, v2
	v_mov_b32_e32 v26, v2
	v_mov_b32_e32 v27, v2
	v_mov_b32_e32 v28, v2
	v_mov_b32_e32 v29, v2
	v_mov_b32_e32 v30, v2
	v_mov_b32_e32 v31, v2
	v_mov_b32_e32 v32, v2
	v_mov_b32_e32 v33, v2
	s_mov_b32 s56, s17
	v_readlane_b32 s79, v254, 61
	s_waitcnt vmcnt(0)
	s_branch .LBB0_644

; #define LAS __attribute__((address_space(3)))
; __device__ __forceinline__ unsigned pk_bf16(float lo, float hi) { f32x2 v; v.x = lo; v.y = hi; const bf16x2_t b = __builtin_convertvector(v, bf16x2_t); return __builtin_bit_cast(unsigned, b); }
; __device__ __forceinline__ void phase_gla(const Frame& F, int l, int gi, int ng, bool last, unsigned* cw) {
;     ...
;         for (int s = 0; s < 68; ++s) {
;             *(LAS u32x4*)(lds + GL_RQ + (li * 136 + ls * 16) * 2) = pq0; *(LAS u32x4*)(lds + GL_RQ + (li * 136 + ls * 16 + 8) * 2) = pq1;
;             *(LAS u32x4*)(lds + GL_RK + (li * 136 + ls * 16) * 2) = pk0; *(LAS u32x4*)(lds + GL_RK + (li * 136 + ls * 16 + 8) * 2) = pk1;
;             *(LAS unsigned*)(lds + GL_LR + (li * 16 + ls * 2) * 2) = pk_f16(pg.x, pg.y);
;             { const f16x8 va = __builtin_bit_cast(f16x8, pv0), vb = __builtin_bit_cast(f16x8, pv1);
; #pragma unroll
;               for (int e = 0; e < 8; e += 2) { const unsigned pa = pk_bf16((float)va[e], (float)va[e + 1]), pb = pk_bf16((float)vb[e], (float)vb[e + 1]);
;                   *(LAS unsigned short*)(lds + GL_VT + ((vs * 16 + e) * 72 + vi) * 2) = (unsigned short)(pa & 0xffffu);
;                   *(LAS unsigned short*)(lds + GL_VT + ((vs * 16 + e + 1) * 72 + vi) * 2) = (unsigned short)(pa >> 16);
;                   *(LAS unsigned short*)(lds + GL_VT + ((vs * 16 + 8 + e) * 72 + vi) * 2) = (unsigned short)(pb & 0xffffu);
;                   *(LAS unsigned short*)(lds + GL_VT + ((vs * 16 + 8 + e + 1) * 72 + vi) * 2) = (unsigned short)(pb >> 16); } }
;             __syncthreads();
.LBB0_644:
	s_waitcnt vmcnt(16)
	v_cvt_pk_f16_f32 v34, v118, v119
	ds_write_b128 v137, v[70:73]
	ds_write_b128 v137, v[74:77] offset:16
	ds_write_b128 v137, v[82:85] offset:17408
	ds_write_b128 v137, v[78:81] offset:17424
	ds_write_b32 v138, v34 offset:34816
	v_cvt_f32_f16_sdwa v34, v86 dst_sel:DWORD dst_unused:UNUSED_PAD src0_sel:WORD_1
	v_cvt_f32_f16_e32 v35, v86
	v_cvt_f32_f16_e32 v36, v90
	s_add_i32 s14, s7, 4
	s_cmp_eq_u32 s7, 63
	v_cvt_pk_bf16_f32 v34, v35, v34
	v_cvt_f32_f16_sdwa v35, v90 dst_sel:DWORD dst_unused:UNUSED_PAD src0_sel:WORD_1
	v_cvt_pk_bf16_f32 v35, v36, v35
	ds_write_b16 v139, v34
	ds_write_b16_d16_hi v140, v34
	ds_write_b16 v141, v35
	ds_write_b16_d16_hi v142, v35
	v_cvt_f32_f16_sdwa v34, v87 dst_sel:DWORD dst_unused:UNUSED_PAD src0_sel:WORD_1
	v_cvt_f32_f16_e32 v35, v87
	v_cvt_f32_f16_e32 v36, v91
	v_cvt_pk_bf16_f32 v34, v35, v34
	v_cvt_f32_f16_sdwa v35, v91 dst_sel:DWORD dst_unused:UNUSED_PAD src0_sel:WORD_1
	v_cvt_pk_bf16_f32 v35, v36, v35
	ds_write_b16 v143, v34
	ds_write_b16_d16_hi v144, v34
	ds_write_b16 v145, v35
	ds_write_b16_d16_hi v146, v35
	v_cvt_f32_f16_sdwa v34, v88 dst_sel:DWORD dst_unused:UNUSED_PAD src0_sel:WORD_1
	v_cvt_f32_f16_e32 v35, v88
	v_cvt_f32_f16_e32 v36, v92
	v_cvt_pk_bf16_f32 v34, v35, v34
	v_cvt_f32_f16_sdwa v35, v92 dst_sel:DWORD dst_unused:UNUSED_PAD src0_sel:WORD_1
	v_cvt_pk_bf16_f32 v35, v36, v35
	ds_write_b16 v147, v34
	ds_write_b16_d16_hi v148, v34
	ds_write_b16 v149, v35
	ds_write_b16_d16_hi v150, v35
	v_cvt_f32_f16_sdwa v34, v89 dst_sel:DWORD dst_unused:UNUSED_PAD src0_sel:WORD_1
	v_cvt_f32_f16_e32 v35, v89
	v_cvt_f32_f16_e32 v36, v93
	v_cvt_pk_bf16_f32 v34, v35, v34
	v_cvt_f32_f16_sdwa v35, v93 dst_sel:DWORD dst_unused:UNUSED_PAD src0_sel:WORD_1
	v_cvt_pk_bf16_f32 v35, v36, v35
	ds_write_b16 v151, v34
	ds_write_b16_d16_hi v152, v34
	ds_write_b16 v153, v35
	ds_write_b16_d16_hi v154, v35
	s_waitcnt lgkmcnt(0)
	s_barrier
	s_cbranch_scc1 .LBB0_654
	s_cmp_gt_u32 s14, 2
	s_cselect_b64 s[2:3], -1, 0
	s_mov_b64 s[12:13], -1
	s_and_b64 vcc, exec, s[2:3]
	s_cbranch_vccz .LBB0_647
	s_add_i32 s0, s7, 1
	s_and_b64 s[12:13], s[84:85], exec
	s_cselect_b32 s0, s0, s37
	s_mov_b64 s[12:13], 0
